# static s_setprio 1 for waves 4-7 (younger half) before the attention loop, no per-segment priority flips
# speedup vs baseline: 1.0090x; 1.0090x over previous
; #define AT_BAR() do { __builtin_amdgcn_sched_barrier(0); asm volatile("s_waitcnt lgkmcnt(0)\n\ts_barrier" ::: "memory"); __builtin_amdgcn_sched_barrier(0); } while (0)
; __device__ __forceinline__ void attn_phase(LAS unsigned char* lds, const bf16_t* Qb, const bf16_t* Kimg, const bf16_t* Vimg, bf16_t* AB, int bid, int G, int wave_k) {
;     ...
;         int b_prev = 2 * AT_BUF, b_cur = 0, b_next = AT_BUF;
;         AT_ISSUE(0, 0); AT_ISSUE(1, AT_BUF);
;         asm volatile("s_waitcnt vmcnt(0)" ::: "memory"); AT_BAR();
;         if (grpB) AT_BAR();
;         for (int t = 0; t < 256; ++t) {
.LBB0_962:
	s_waitcnt lgkmcnt(0)
	s_barrier
	s_add_u32 s0, s0, 0x6000
	s_addc_u32 s1, s1, 0
	s_mul_i32 s16, s55, 3
	s_add_u32 s18, s18, s16
	s_addc_u32 s19, s19, 0
	s_add_u32 s20, s20, 0x9000
	s_addc_u32 s21, s21, 0
	s_mov_b32 s61, 1
	s_mov_b32 s63, 0xa000
	s_movk_i32 s62, 0x5000
	s_mov_b32 s16, 0
	v_mov_b32_e32 v65, v64
	v_mov_b32_e32 v66, v64
	v_mov_b32_e32 v67, v64
	v_mov_b32_e32 v68, v64
	v_mov_b32_e32 v69, v64
	v_mov_b32_e32 v70, v64
	v_mov_b32_e32 v71, v64
	v_mov_b32_e32 v72, v64
	v_mov_b32_e32 v73, v64
	v_mov_b32_e32 v74, v64
	v_mov_b32_e32 v75, v64
	v_mov_b32_e32 v76, v64
	v_mov_b32_e32 v77, v64
	v_mov_b32_e32 v78, v64
	v_mov_b32_e32 v79, v64
	v_mov_b32_e32 v234, v223
	v_mov_b32_e32 v237, v222
	s_bitcmp1_b32 s42, 0
	s_cbranch_scc0 .Lat_prio_skip
	s_setprio 1
.Lat_prio_skip:
	s_mov_b32 s64, s16
	v_add_u32_e32 v160, s62, v236
	v_add_u32_e32 v128, s64, v236

; #define AT_BAR() do { __builtin_amdgcn_sched_barrier(0); asm volatile("s_waitcnt lgkmcnt(0)\n\ts_barrier" ::: "memory"); __builtin_amdgcn_sched_barrier(0); } while (0)
; __device__ __forceinline__ void attn_phase(LAS unsigned char* lds, const bf16_t* Qb, const bf16_t* Kimg, const bf16_t* Vimg, bf16_t* AB, int bid, int G, int wave_k) {
;     ...
;         AT_PV(b_prev, 2);
;         if (!grpB) AT_BAR();
;         AT_BAR();
.LBB0_983:
	s_setprio 0
	v_mov_b32_e32 v223, v234
	v_mov_b32_e32 v222, v237
	v_add_u32_e32 v72, s64, v236
	ds_read_b128 v[64:67], v72 offset:16384
	ds_read_b128 v[68:71], v72 offset:16896
	s_and_b64 vcc, s[14:15], exec
	s_waitcnt lgkmcnt(0)
	v_mfma_f32_32x32x16_bf16 v[48:63], v[64:67], v[116:119], v[48:63]
	v_mfma_f32_32x32x16_bf16 v[32:47], v[68:71], v[116:119], v[32:47]
	v_mfma_f32_32x32x16_bf16 v[16:31], v[64:67], v[100:103], v[16:31]
	v_mfma_f32_32x32x16_bf16 v[0:15], v[68:71], v[100:103], v[0:15]
	ds_read_b128 v[64:67], v72 offset:18432
	ds_read_b128 v[68:71], v72 offset:18944
	s_waitcnt lgkmcnt(0)
	v_mfma_f32_32x32x16_bf16 v[48:63], v[64:67], v[112:115], v[48:63]
	v_mfma_f32_32x32x16_bf16 v[32:47], v[68:71], v[112:115], v[32:47]
	v_mfma_f32_32x32x16_bf16 v[16:31], v[64:67], v[96:99], v[16:31]
	v_mfma_f32_32x32x16_bf16 v[0:15], v[68:71], v[96:99], v[0:15]
	s_cbranch_vccz .LBB0_947
	s_waitcnt lgkmcnt(0)
	s_barrier
	s_branch .LBB0_947
